# v52 + P6 LN-epilogue pass 1 step order 0,2,1,3,4,6,5,7: the two 64-byte halves of each 128-byte line of x are now requested in adjacent steps
# speedup vs baseline: 1.0150x; 1.0065x over previous
;     __device__ __forceinline__ void fused(f32x4 (&acc)[2][2][4][2], const Unit& u, int wr, int wc, int fr, int fq, PG8_LAS unsigned char* lds, int wid, int lane) const {
;     ...
;         for (int m = 0; m < 4; ++m) xc[m] = __builtin_nontemporal_load((const f32x4*)(xp + (size_t)(m * 16) * D));
; #pragma unroll
;         for (int g = 0; g < 8; ++g) { const int bj = g >> 2, n = (g >> 1) & 1, ai = g & 1; const int c = col0 + bj * 128 + n * 16;
;             if (g < 7) { const int g1 = g + 1, bj1 = g1 >> 2, n1 = (g1 >> 1) & 1, ai1 = g1 & 1;
; #pragma unroll
;                 for (int m = 0; m < 4; ++m) xn[m] = __builtin_nontemporal_load((const f32x4*)(xp + (size_t)(ai1 * 128 + m * 16) * D + bj1 * 128 + n1 * 16)); }
;             const f32x4 gv = *(const f32x4*)(gate + c), bv = *(const f32x4*)(bo + c);
;             asm volatile("" ::: "memory");
; #pragma unroll
;             for (int m = 0; m < 4; ++m) acc[ai][bj][m][n] = xc[m] * ALPHA + gv * (acc[ai][bj][m][n] + bv);
;             asm volatile("" : "+v"(acc[ai][bj][0][n]), "+v"(acc[ai][bj][1][n]), "+v"(acc[ai][bj][2][n]), "+v"(acc[ai][bj][3][n]));
;             asm volatile("" ::: "memory");
; #pragma unroll
;             for (int m = 0; m < 4; ++m) xc[m] = xn[m]; }
.LBB0_496:
	s_lshl_b32 s0, s39, 5
	s_lshl_b32 s1, s4, 8
	s_or_b32 s0, s1, s0
	v_lshrrev_b32_e32 v128, 2, v174
	v_and_or_b32 v166, v128, 12, s0
	s_lshl_b32 s6, s38, 8
	v_mov_b32_e32 v128, v149
	s_barrier
	v_add_u32_e32 v152, s6, v153
	v_add_u32_e32 v128, v128, v152
	v_ashrrev_i32_e32 v129, 31, v128
	v_lshlrev_b64 v[128:129], 12, v[128:129]
	v_ashrrev_i32_e32 v167, 31, v166
	s_ashr_i32 s0, s38, 3
	v_lshlrev_b64 v[154:155], 2, v[166:167]
	v_lshl_add_u64 v[128:129], s[76:77], 0, v[128:129]
	s_mul_hi_i32 s1, s0, 0x3000
	s_mulk_i32 s0, 0x3000
	v_lshl_add_u64 v[140:141], v[128:129], 0, v[154:155]
	s_add_u32 s0, s96, s0
	v_add_co_u32_e32 v136, vcc, s51, v140
	s_addc_u32 s1, s97, s1
	v_readlane_b32 s60, v250, 0
	v_addc_co_u32_e32 v137, vcc, 0, v141, vcc
	v_readlane_b32 s64, v250, 4
	v_readlane_b32 s65, v250, 5
	s_add_u32 s0, s0, 0x2000
	v_add_co_u32_e32 v128, vcc, s52, v140
	v_lshl_add_u64 v[156:157], s[64:65], 0, v[154:155]
	s_addc_u32 s1, s1, 0
	v_addc_co_u32_e32 v129, vcc, 0, v141, vcc
	global_load_dwordx4 v[216:219], v[156:157], off
	global_load_dwordx4 v[220:223], v[156:157], off offset:64
	global_load_dwordx4 v[224:227], v[156:157], off offset:512
	global_load_dwordx4 v[228:231], v[156:157], off offset:576
	v_lshl_add_u64 v[138:139], s[0:1], 0, v[154:155]
	v_add_co_u32_e32 v130, vcc, s53, v140
	global_load_dwordx4 v[232:235], v[138:139], off
	global_load_dwordx4 v[236:239], v[138:139], off offset:64
	global_load_dwordx4 v[240:243], v[138:139], off offset:512
	global_load_dwordx4 v[244:247], v[138:139], off offset:576
	s_nop 0
	v_addc_co_u32_e32 v131, vcc, 0, v141, vcc
	global_load_dwordx4 v[180:183], v[140:141], off nt
	global_load_dwordx4 v[184:187], v[136:137], off nt
	global_load_dwordx4 v[188:191], v[128:129], off nt
	global_load_dwordx4 v[192:195], v[130:131], off nt
	v_add_co_u32_e32 v158, vcc, s54, v140
	v_xor_b32_e32 v148, 16, v172
	s_nop 0
	v_addc_co_u32_e32 v159, vcc, 0, v141, vcc
	v_add_co_u32_e32 v160, vcc, s55, v140
	v_readlane_b32 s61, v250, 1
	s_nop 0
	v_addc_co_u32_e32 v161, vcc, 0, v141, vcc
	v_add_co_u32_e32 v162, vcc, s56, v140
	v_readlane_b32 s62, v250, 2
	s_nop 0
	v_addc_co_u32_e32 v163, vcc, 0, v141, vcc
	v_add_co_u32_e32 v164, vcc, s57, v140
	v_readlane_b32 s63, v250, 3
	s_nop 0
	v_addc_co_u32_e32 v165, vcc, 0, v141, vcc
	global_load_dwordx4 v[196:199], v[130:131], off offset:64 nt
	global_load_dwordx4 v[200:203], v[128:129], off offset:64 nt
	global_load_dwordx4 v[204:207], v[136:137], off offset:64 nt
	global_load_dwordx4 v[208:211], v[140:141], off offset:64 nt
	v_readlane_b32 s66, v250, 6
	v_readlane_b32 s67, v250, 7
	s_waitcnt vmcnt(4)
	v_pk_add_f32 v[82:83], v[82:83], v[218:219]
	v_pk_add_f32 v[80:81], v[80:81], v[216:217]
	v_pk_add_f32 v[78:79], v[78:79], v[218:219]
	v_pk_add_f32 v[76:77], v[76:77], v[216:217]
	v_pk_add_f32 v[66:67], v[66:67], v[218:219]
	v_pk_add_f32 v[64:65], v[64:65], v[216:217]
	v_pk_add_f32 v[62:63], v[62:63], v[218:219]
	v_pk_add_f32 v[60:61], v[60:61], v[216:217]
	v_pk_mul_f32 v[82:83], v[234:235], v[82:83]
	v_pk_mul_f32 v[80:81], v[232:233], v[80:81]
	v_pk_mul_f32 v[78:79], v[234:235], v[78:79]
	v_pk_mul_f32 v[76:77], v[232:233], v[76:77]
	v_pk_mul_f32 v[66:67], v[234:235], v[66:67]
	v_pk_mul_f32 v[64:65], v[232:233], v[64:65]
	v_pk_mul_f32 v[132:133], v[234:235], v[62:63]
	v_pk_mul_f32 v[134:135], v[232:233], v[60:61]
	v_pk_fma_f32 v[82:83], v[182:183], s[34:35], v[82:83] op_sel_hi:[1,0,1]
	v_pk_fma_f32 v[80:81], v[180:181], s[34:35], v[80:81] op_sel_hi:[1,0,1]
	v_pk_fma_f32 v[78:79], v[186:187], s[34:35], v[78:79] op_sel_hi:[1,0,1]
	v_pk_fma_f32 v[76:77], v[184:185], s[34:35], v[76:77] op_sel_hi:[1,0,1]
	v_pk_fma_f32 v[62:63], v[190:191], s[34:35], v[66:67] op_sel_hi:[1,0,1]
	v_pk_fma_f32 v[60:61], v[188:189], s[34:35], v[64:65] op_sel_hi:[1,0,1]
	v_pk_fma_f32 v[66:67], v[194:195], s[34:35], v[132:133] op_sel_hi:[1,0,1]
	v_pk_fma_f32 v[64:65], v[192:193], s[34:35], v[134:135] op_sel_hi:[1,0,1]
	s_nop 0
	global_load_dwordx4 v[180:183], v[158:159], off nt
	global_load_dwordx4 v[184:187], v[160:161], off nt
	global_load_dwordx4 v[188:191], v[162:163], off nt
	global_load_dwordx4 v[192:195], v[164:165], off nt
	v_or_b32_e32 v138, 16, v166
	v_ashrrev_i32_e32 v139, 31, v138
	v_lshl_add_u64 v[138:139], v[138:139], 2, s[0:1]
	s_waitcnt vmcnt(4)
	v_pk_add_f32 v[86:87], v[86:87], v[222:223]
	v_pk_add_f32 v[84:85], v[84:85], v[220:221]
	v_pk_add_f32 v[54:55], v[54:55], v[222:223]
	v_pk_add_f32 v[52:53], v[52:53], v[220:221]
	v_pk_add_f32 v[34:35], v[34:35], v[222:223]
	v_pk_add_f32 v[32:33], v[32:33], v[220:221]
	v_pk_add_f32 v[18:19], v[18:19], v[222:223]
	v_pk_add_f32 v[16:17], v[16:17], v[220:221]
	s_waitcnt vmcnt(4)
	v_pk_mul_f32 v[86:87], v[238:239], v[86:87]
	v_pk_mul_f32 v[84:85], v[236:237], v[84:85]
	v_pk_mul_f32 v[54:55], v[238:239], v[54:55]
	v_pk_mul_f32 v[52:53], v[236:237], v[52:53]
	v_pk_mul_f32 v[34:35], v[238:239], v[34:35]
	v_pk_mul_f32 v[32:33], v[236:237], v[32:33]
	v_pk_mul_f32 v[18:19], v[238:239], v[18:19]
	v_pk_mul_f32 v[16:17], v[236:237], v[16:17]
	v_pk_fma_f32 v[86:87], v[210:211], s[34:35], v[86:87] op_sel_hi:[1,0,1]
	v_pk_fma_f32 v[84:85], v[208:209], s[34:35], v[84:85] op_sel_hi:[1,0,1]
	v_pk_fma_f32 v[54:55], v[206:207], s[34:35], v[54:55] op_sel_hi:[1,0,1]
	v_pk_fma_f32 v[52:53], v[204:205], s[34:35], v[52:53] op_sel_hi:[1,0,1]
	v_pk_fma_f32 v[34:35], v[202:203], s[34:35], v[34:35] op_sel_hi:[1,0,1]
	v_pk_fma_f32 v[32:33], v[200:201], s[34:35], v[32:33] op_sel_hi:[1,0,1]
	v_pk_fma_f32 v[18:19], v[198:199], s[34:35], v[18:19] op_sel_hi:[1,0,1]
	v_pk_fma_f32 v[16:17], v[196:197], s[34:35], v[16:17] op_sel_hi:[1,0,1]
	s_nop 0
	global_load_dwordx4 v[196:199], v[158:159], off offset:64 nt
	global_load_dwordx4 v[200:203], v[160:161], off offset:64 nt
	global_load_dwordx4 v[204:207], v[162:163], off offset:64 nt
	global_load_dwordx4 v[208:211], v[164:165], off offset:64 nt
	s_waitcnt vmcnt(4)
;     __device__ __forceinline__ void fused(f32x4 (&acc)[2][2][4][2], const Unit& u, int wr, int wc, int fr, int fq, PG8_LAS unsigned char* lds, int wid, int lane) const {
;     ...
;         for (int g = 0; g < 8; ++g) { const int bj = g >> 2, n = (g >> 1) & 1, ai = g & 1; const int c = col0 + bj * 128 + n * 16;
;             if (g < 7) { const int g1 = g + 1, bj1 = g1 >> 2, n1 = (g1 >> 1) & 1, ai1 = g1 & 1;
; #pragma unroll
;                 for (int m = 0; m < 4; ++m) xn[m] = __builtin_nontemporal_load((const f32x4*)(xp + (size_t)(ai1 * 128 + m * 16) * D + bj1 * 128 + n1 * 16)); }
;             const f32x4 gv = *(const f32x4*)(gate + c), bv = *(const f32x4*)(bo + c);
;             asm volatile("" ::: "memory");
; #pragma unroll
;             for (int m = 0; m < 4; ++m) acc[ai][bj][m][n] = xc[m] * ALPHA + gv * (acc[ai][bj][m][n] + bv);
;             asm volatile("" : "+v"(acc[ai][bj][0][n]), "+v"(acc[ai][bj][1][n]), "+v"(acc[ai][bj][2][n]), "+v"(acc[ai][bj][3][n]));
;             asm volatile("" ::: "memory");
; #pragma unroll
;             for (int m = 0; m < 4; ++m) xc[m] = xn[m]; }
	v_pk_add_f32 v[94:95], v[94:95], v[218:219]
	v_pk_add_f32 v[92:93], v[92:93], v[216:217]
	v_pk_add_f32 v[90:91], v[90:91], v[218:219]
	v_pk_add_f32 v[88:89], v[88:89], v[216:217]
	v_pk_add_f32 v[46:47], v[46:47], v[218:219]
	v_pk_add_f32 v[44:45], v[44:45], v[216:217]
	v_pk_add_f32 v[30:31], v[30:31], v[218:219]
	v_pk_add_f32 v[28:29], v[28:29], v[216:217]
	s_waitcnt vmcnt(4)
	v_pk_mul_f32 v[94:95], v[234:235], v[94:95]
	v_pk_mul_f32 v[92:93], v[232:233], v[92:93]
	v_pk_mul_f32 v[90:91], v[234:235], v[90:91]
	v_pk_mul_f32 v[88:89], v[232:233], v[88:89]
	v_pk_mul_f32 v[46:47], v[234:235], v[46:47]
	v_pk_mul_f32 v[44:45], v[232:233], v[44:45]
	v_pk_mul_f32 v[30:31], v[234:235], v[30:31]
	v_pk_mul_f32 v[28:29], v[232:233], v[28:29]
	v_pk_fma_f32 v[94:95], v[194:195], s[34:35], v[94:95] op_sel_hi:[1,0,1]
	v_pk_fma_f32 v[92:93], v[192:193], s[34:35], v[92:93] op_sel_hi:[1,0,1]
	v_pk_fma_f32 v[90:91], v[190:191], s[34:35], v[90:91] op_sel_hi:[1,0,1]
	v_pk_fma_f32 v[88:89], v[188:189], s[34:35], v[88:89] op_sel_hi:[1,0,1]
	v_pk_fma_f32 v[46:47], v[186:187], s[34:35], v[46:47] op_sel_hi:[1,0,1]
	v_pk_fma_f32 v[44:45], v[184:185], s[34:35], v[44:45] op_sel_hi:[1,0,1]
	v_pk_fma_f32 v[30:31], v[182:183], s[34:35], v[30:31] op_sel_hi:[1,0,1]
	v_pk_fma_f32 v[28:29], v[180:181], s[34:35], v[28:29] op_sel_hi:[1,0,1]
	s_nop 0
	global_load_dwordx4 v[180:183], v[130:131], off offset:512 nt
	global_load_dwordx4 v[184:187], v[128:129], off offset:512 nt
	global_load_dwordx4 v[188:191], v[136:137], off offset:512 nt
	global_load_dwordx4 v[192:195], v[140:141], off offset:512 nt
	v_or_b32_e32 v138, 0x80, v166
	v_ashrrev_i32_e32 v139, 31, v138
	v_lshl_add_u64 v[138:139], v[138:139], 2, s[0:1]
	v_or_b32_e32 v166, 0x90, v166
	v_ashrrev_i32_e32 v167, 31, v166
	s_waitcnt vmcnt(4)
	v_pk_add_f32 v[70:71], v[70:71], v[222:223]
	v_pk_add_f32 v[68:69], v[68:69], v[220:221]
	v_pk_add_f32 v[50:51], v[50:51], v[222:223]
	v_pk_add_f32 v[48:49], v[48:49], v[220:221]
	v_pk_add_f32 v[26:27], v[26:27], v[222:223]
	v_pk_add_f32 v[24:25], v[24:25], v[220:221]
	v_pk_add_f32 v[10:11], v[10:11], v[222:223]
	v_pk_add_f32 v[8:9], v[8:9], v[220:221]
	s_waitcnt vmcnt(4)
	v_pk_mul_f32 v[70:71], v[238:239], v[70:71]
	v_pk_mul_f32 v[68:69], v[236:237], v[68:69]
	v_pk_mul_f32 v[50:51], v[238:239], v[50:51]
	v_pk_mul_f32 v[48:49], v[236:237], v[48:49]
	v_pk_mul_f32 v[26:27], v[238:239], v[26:27]
	v_pk_mul_f32 v[24:25], v[236:237], v[24:25]
	v_pk_mul_f32 v[10:11], v[238:239], v[10:11]
	v_pk_mul_f32 v[8:9], v[236:237], v[8:9]
	v_pk_fma_f32 v[70:71], v[210:211], s[34:35], v[70:71] op_sel_hi:[1,0,1]
	v_pk_fma_f32 v[68:69], v[208:209], s[34:35], v[68:69] op_sel_hi:[1,0,1]
	v_pk_fma_f32 v[50:51], v[206:207], s[34:35], v[50:51] op_sel_hi:[1,0,1]
	v_pk_fma_f32 v[48:49], v[204:205], s[34:35], v[48:49] op_sel_hi:[1,0,1]
	v_pk_fma_f32 v[26:27], v[202:203], s[34:35], v[26:27] op_sel_hi:[1,0,1]
	v_pk_fma_f32 v[24:25], v[200:201], s[34:35], v[24:25] op_sel_hi:[1,0,1]
	v_pk_fma_f32 v[10:11], v[198:199], s[34:35], v[10:11] op_sel_hi:[1,0,1]
	v_pk_fma_f32 v[8:9], v[196:197], s[34:35], v[8:9] op_sel_hi:[1,0,1]
	s_nop 0
	global_load_dwordx4 v[132:135], v[128:129], off offset:576 nt
	s_nop 0
	global_load_dwordx4 v[128:131], v[130:131], off offset:576 nt
	s_nop 0
	global_load_dwordx4 v[136:139], v[136:137], off offset:576 nt
	s_nop 0
	global_load_dwordx4 v[140:143], v[140:141], off offset:576 nt
	s_waitcnt vmcnt(4)
	v_pk_add_f32 v[74:75], v[74:75], v[226:227]
	v_pk_add_f32 v[72:73], v[72:73], v[224:225]
	v_pk_add_f32 v[42:43], v[42:43], v[226:227]
	v_pk_add_f32 v[40:41], v[40:41], v[224:225]
	v_pk_add_f32 v[22:23], v[22:23], v[226:227]
	v_pk_add_f32 v[20:21], v[20:21], v[224:225]
	v_pk_add_f32 v[6:7], v[6:7], v[226:227]
	v_pk_add_f32 v[4:5], v[4:5], v[224:225]
	s_waitcnt vmcnt(4)
	v_pk_mul_f32 v[74:75], v[242:243], v[74:75]
	v_pk_mul_f32 v[72:73], v[240:241], v[72:73]
	v_pk_mul_f32 v[42:43], v[242:243], v[42:43]
	v_pk_mul_f32 v[40:41], v[240:241], v[40:41]
	v_pk_mul_f32 v[22:23], v[242:243], v[22:23]
	v_pk_mul_f32 v[20:21], v[240:241], v[20:21]
	v_pk_mul_f32 v[6:7], v[242:243], v[6:7]
	v_pk_mul_f32 v[4:5], v[240:241], v[4:5]
	v_pk_fma_f32 v[74:75], v[194:195], s[34:35], v[74:75] op_sel_hi:[1,0,1]
	v_pk_fma_f32 v[72:73], v[192:193], s[34:35], v[72:73] op_sel_hi:[1,0,1]
	v_pk_fma_f32 v[42:43], v[190:191], s[34:35], v[42:43] op_sel_hi:[1,0,1]
	v_pk_fma_f32 v[40:41], v[188:189], s[34:35], v[40:41] op_sel_hi:[1,0,1]
	v_pk_fma_f32 v[22:23], v[186:187], s[34:35], v[22:23] op_sel_hi:[1,0,1]
	v_pk_fma_f32 v[20:21], v[184:185], s[34:35], v[20:21] op_sel_hi:[1,0,1]
	v_pk_fma_f32 v[6:7], v[182:183], s[34:35], v[6:7] op_sel_hi:[1,0,1]
	v_pk_fma_f32 v[4:5], v[180:181], s[34:35], v[4:5] op_sel_hi:[1,0,1]
	v_lshl_add_u64 v[192:193], v[166:167], 2, s[0:1]
	global_load_dwordx4 v[176:179], v[158:159], off offset:512 nt
	global_load_dwordx4 v[200:203], v[160:161], off offset:512 nt
	global_load_dwordx4 v[204:207], v[162:163], off offset:512 nt
	global_load_dwordx4 v[208:211], v[164:165], off offset:512 nt
	v_and_b32_e32 v166, 64, v172
	v_mov_b32_e32 v194, v81
	v_mov_b32_e32 v195, v82
	s_lshl_b32 s0, s39, 3
	s_add_i32 s7, s0, 0
	s_waitcnt vmcnt(4)
	v_pk_add_f32 v[118:119], v[118:119], v[230:231]
	v_pk_add_f32 v[116:117], v[116:117], v[228:229]
	v_pk_add_f32 v[110:111], v[110:111], v[230:231]
	v_pk_add_f32 v[108:109], v[108:109], v[228:229]
	v_pk_add_f32 v[102:103], v[102:103], v[230:231]
	v_pk_add_f32 v[100:101], v[100:101], v[228:229]
	v_pk_add_f32 v[98:99], v[98:99], v[230:231]
	v_pk_add_f32 v[96:97], v[96:97], v[228:229]
	s_waitcnt vmcnt(4)
;     __device__ __forceinline__ bool run(const f32x4 (&v)[2][2][4][2], const Unit& u, int wr, int wc, int fr, int fq, PG8_LAS unsigned char* lds, int wid, int lane) const {
;     ...
;                     for (int n = 0; n < 2; ++n) { const f32x4 x = v[ai][bj][m][n]; s += (x[0] + x[1]) + (x[2] + x[3]); }
;                 s += __shfl_xor(s, 16); s += __shfl_xor(s, 32);
;     __device__ __forceinline__ void fused(f32x4 (&acc)[2][2][4][2], const Unit& u, int wr, int wc, int fr, int fq, PG8_LAS unsigned char* lds, int wid, int lane) const {
;     ...
;         for (int g = 0; g < 8; ++g) { const int bj = g >> 2, n = (g >> 1) & 1, ai = g & 1; const int c = col0 + bj * 128 + n * 16;
;             if (g < 7) { const int g1 = g + 1, bj1 = g1 >> 2, n1 = (g1 >> 1) & 1, ai1 = g1 & 1;
; #pragma unroll
;                 for (int m = 0; m < 4; ++m) xn[m] = __builtin_nontemporal_load((const f32x4*)(xp + (size_t)(ai1 * 128 + m * 16) * D + bj1 * 128 + n1 * 16)); }
;             const f32x4 gv = *(const f32x4*)(gate + c), bv = *(const f32x4*)(bo + c);
;             asm volatile("" ::: "memory");
; #pragma unroll
;             for (int m = 0; m < 4; ++m) acc[ai][bj][m][n] = xc[m] * ALPHA + gv * (acc[ai][bj][m][n] + bv);
;             asm volatile("" : "+v"(acc[ai][bj][0][n]), "+v"(acc[ai][bj][1][n]), "+v"(acc[ai][bj][2][n]), "+v"(acc[ai][bj][3][n]));
;             asm volatile("" ::: "memory");
; #pragma unroll
;             for (int m = 0; m < 4; ++m) xc[m] = xn[m]; }
	v_pk_mul_f32 v[118:119], v[246:247], v[118:119]
	v_pk_mul_f32 v[116:117], v[244:245], v[116:117]
	v_pk_mul_f32 v[110:111], v[246:247], v[110:111]
	v_pk_mul_f32 v[108:109], v[244:245], v[108:109]
	v_pk_mul_f32 v[102:103], v[246:247], v[102:103]
	v_pk_mul_f32 v[100:101], v[244:245], v[100:101]
	v_pk_mul_f32 v[98:99], v[246:247], v[98:99]
	v_pk_mul_f32 v[96:97], v[244:245], v[96:97]
	v_pk_fma_f32 v[118:119], v[142:143], s[34:35], v[118:119] op_sel_hi:[1,0,1]
	v_pk_fma_f32 v[116:117], v[140:141], s[34:35], v[116:117] op_sel_hi:[1,0,1]
	v_pk_fma_f32 v[110:111], v[138:139], s[34:35], v[110:111] op_sel_hi:[1,0,1]
	v_pk_fma_f32 v[108:109], v[136:137], s[34:35], v[108:109] op_sel_hi:[1,0,1]
	v_pk_fma_f32 v[102:103], v[134:135], s[34:35], v[102:103] op_sel_hi:[1,0,1]
	v_pk_fma_f32 v[100:101], v[132:133], s[34:35], v[100:101] op_sel_hi:[1,0,1]
	v_pk_fma_f32 v[98:99], v[130:131], s[34:35], v[98:99] op_sel_hi:[1,0,1]
	v_pk_fma_f32 v[96:97], v[128:129], s[34:35], v[96:97] op_sel_hi:[1,0,1]
	v_add_u32_e32 v198, 64, v166
	s_nop 0
	global_load_dwordx4 v[164:167], v[164:165], off offset:576 nt
	s_nop 0
	global_load_dwordx4 v[184:187], v[162:163], off offset:576 nt
	s_nop 0
	global_load_dwordx4 v[160:163], v[160:161], off offset:576 nt
	s_nop 0
	global_load_dwordx4 v[188:191], v[158:159], off offset:576 nt
	v_mov_b32_e32 v196, v80
	v_mov_b32_e32 v197, v83
	v_cmp_lt_i32_e32 vcc, v148, v198
	s_waitcnt vmcnt(4)
	v_pk_add_f32 v[58:59], v[58:59], v[226:227]
	v_pk_add_f32 v[56:57], v[56:57], v[224:225]
	v_pk_add_f32 v[38:39], v[38:39], v[226:227]
	v_pk_add_f32 v[36:37], v[36:37], v[224:225]
	v_pk_add_f32 v[14:15], v[14:15], v[226:227]
	v_pk_add_f32 v[12:13], v[12:13], v[224:225]
	v_pk_add_f32 v[2:3], v[2:3], v[226:227]
	v_pk_add_f32 v[0:1], v[0:1], v[224:225]
	s_waitcnt vmcnt(4)
	v_pk_mul_f32 v[58:59], v[242:243], v[58:59]
	v_pk_mul_f32 v[56:57], v[240:241], v[56:57]
	v_pk_mul_f32 v[38:39], v[242:243], v[38:39]
	v_pk_mul_f32 v[36:37], v[240:241], v[36:37]
	v_pk_mul_f32 v[14:15], v[242:243], v[14:15]
	v_pk_mul_f32 v[12:13], v[240:241], v[12:13]
	v_pk_mul_f32 v[2:3], v[242:243], v[2:3]
	v_pk_mul_f32 v[0:1], v[240:241], v[0:1]
	v_pk_fma_f32 v[58:59], v[210:211], s[34:35], v[58:59] op_sel_hi:[1,0,1]
	v_pk_fma_f32 v[56:57], v[208:209], s[34:35], v[56:57] op_sel_hi:[1,0,1]
	v_pk_fma_f32 v[38:39], v[206:207], s[34:35], v[38:39] op_sel_hi:[1,0,1]
	v_pk_fma_f32 v[36:37], v[204:205], s[34:35], v[36:37] op_sel_hi:[1,0,1]
	v_pk_fma_f32 v[14:15], v[202:203], s[34:35], v[14:15] op_sel_hi:[1,0,1]
	v_pk_fma_f32 v[12:13], v[200:201], s[34:35], v[12:13] op_sel_hi:[1,0,1]
	v_pk_fma_f32 v[2:3], v[178:179], s[34:35], v[2:3] op_sel_hi:[1,0,1]
	v_pk_fma_f32 v[0:1], v[176:177], s[34:35], v[0:1] op_sel_hi:[1,0,1]
	v_mov_b32_e32 v130, v85
	v_mov_b32_e32 v131, v86
	v_mov_b32_e32 v132, v84
	v_mov_b32_e32 v133, v87
	v_pk_add_f32 v[128:129], v[194:195], v[196:197]
	v_pk_add_f32 v[130:131], v[130:131], v[132:133]
	v_add_f32_e32 v128, v128, v129
	v_pk_add_f32 v[130:131], v[130:131], v[130:131] op_sel:[0,1] op_sel_hi:[1,0]
	v_add_f32_e32 v128, 0, v128
	v_add_f32_e32 v132, v72, v73
	v_add_f32_e32 v142, v74, v75
	v_mov_b32_e32 v129, v116
	v_mov_b32_e32 v131, v117
	v_mov_b32_e32 v133, v118
	v_mov_b32_e32 v143, v119
	v_pk_add_f32 v[128:129], v[128:129], v[130:131]
	v_pk_add_f32 v[130:131], v[132:133], v[142:143]
	v_cndmask_b32_e32 v148, v172, v148, vcc
	v_pk_add_f32 v[128:129], v[128:129], v[130:131]
	v_lshlrev_b32_e32 v148, 2, v148
	v_add_f32_e32 v129, v128, v129
	v_mov_b32_e32 v130, v129
	v_mov_b32_e32 v212, v129
	s_nop 1
	v_permlane16_swap_b32_e32 v130, v212
	v_xor_b32_e32 v128, 32, v172
	v_cmp_lt_i32_e32 vcc, v128, v198
	s_waitcnt lgkmcnt(0)
;     __device__ __forceinline__ bool run(const f32x4 (&v)[2][2][4][2], const Unit& u, int wr, int wc, int fr, int fq, PG8_LAS unsigned char* lds, int wid, int lane) const {
;     ...
;                     for (int n = 0; n < 2; ++n) { const f32x4 x = v[ai][bj][m][n]; s += (x[0] + x[1]) + (x[2] + x[3]); }
;                 s += __shfl_xor(s, 16); s += __shfl_xor(s, 32);
;                 const float mw = s * (1.0f / 64.0f); float q = 0.f;
; #pragma unroll
;                 for (int bj = 0; bj < 2; ++bj)
; #pragma unroll
;                     for (int n = 0; n < 2; ++n) { const f32x4 d = v[ai][bj][m][n] - mw; q += (d[0] * d[0] + d[1] * d[1]) + (d[2] * d[2] + d[3] * d[3]); }
;                 q += __shfl_xor(q, 16); q += __shfl_xor(q, 32);
;                 if (fq == 0) P[(ai * HALF + wr * 64 + m * 16 + fr) * 4 + wc] = (f32x2v){mw, q};
;     __device__ __forceinline__ void fused(f32x4 (&acc)[2][2][4][2], const Unit& u, int wr, int wc, int fr, int fq, PG8_LAS unsigned char* lds, int wid, int lane) const {
;     ...
;             for (int m = 0; m < 4; ++m) acc[ai][bj][m][n] = xc[m] * ALPHA + gv * (acc[ai][bj][m][n] + bv);
	v_add_f32_e32 v129, v130, v212
	v_cndmask_b32_e32 v128, v172, v128, vcc
	v_lshlrev_b32_e32 v128, 2, v128
	v_mov_b32_e32 v130, v129
	v_mov_b32_e32 v212, v129
	s_nop 1
	v_permlane32_swap_b32_e32 v130, v212
	s_waitcnt lgkmcnt(0)
	v_add_f32_e32 v129, v130, v212
	v_fmamk_f32 v131, v129, 0xbc800000, v83
	v_fmamk_f32 v133, v129, 0xbc800000, v81
	v_fmamk_f32 v143, v129, 0xbc800000, v87
	v_fmamk_f32 v157, v129, 0xbc800000, v85
	v_fmamk_f32 v130, v129, 0xbc800000, v82
	v_fmamk_f32 v132, v129, 0xbc800000, v80
	v_fmamk_f32 v142, v129, 0xbc800000, v86
	v_fmamk_f32 v156, v129, 0xbc800000, v84
	v_fmamk_f32 v159, v129, 0xbc800000, v75
	v_fmamk_f32 v177, v129, 0xbc800000, v73
	v_mul_f32_e32 v133, v133, v133
	v_mul_f32_e32 v131, v131, v131
	v_mul_f32_e32 v157, v157, v157
	v_mul_f32_e32 v143, v143, v143
	v_fmamk_f32 v158, v129, 0xbc800000, v74
	v_fmamk_f32 v176, v129, 0xbc800000, v72
	v_fmamk_f32 v179, v129, 0xbc800000, v119
	v_fmamk_f32 v181, v129, 0xbc800000, v117
	v_mul_f32_e32 v177, v177, v177
	v_mul_f32_e32 v159, v159, v159
	v_fmac_f32_e32 v133, v132, v132
	v_fmac_f32_e32 v131, v130, v130
	v_fmac_f32_e32 v157, v156, v156
	v_fmac_f32_e32 v143, v142, v142
	v_fmamk_f32 v178, v129, 0xbc800000, v118
	v_fmamk_f32 v180, v129, 0xbc800000, v116
	v_mul_f32_e32 v181, v181, v181
	v_mul_f32_e32 v179, v179, v179
	v_fmac_f32_e32 v177, v176, v176
	v_fmac_f32_e32 v159, v158, v158
	v_add_f32_e32 v130, v133, v131
	v_add_f32_e32 v131, v157, v143
	v_fmac_f32_e32 v181, v180, v180
	v_fmac_f32_e32 v179, v178, v178
	v_add_f32_e32 v132, v177, v159
	v_add_f32_e32 v130, v130, v131
	v_add_f32_e32 v133, v181, v179
	v_add_f32_e32 v130, v132, v130
	v_add_f32_e32 v131, v133, v130
	v_mov_b32_e32 v132, v131
	v_mov_b32_e32 v212, v131
	s_nop 1
	v_permlane16_swap_b32_e32 v132, v212
	v_and_b32_e32 v130, 63, v174
	v_cmp_gt_u32_e32 vcc, 16, v130
	s_waitcnt lgkmcnt(0)
	v_add_f32_e32 v131, v132, v212
	s_waitcnt vmcnt(0)
	v_pk_add_f32 v[126:127], v[126:127], v[230:231]
	v_pk_add_f32 v[124:125], v[124:125], v[228:229]
	v_pk_add_f32 v[122:123], v[122:123], v[230:231]
	v_pk_add_f32 v[120:121], v[120:121], v[228:229]
	v_pk_add_f32 v[114:115], v[114:115], v[230:231]
	v_pk_add_f32 v[112:113], v[112:113], v[228:229]
	v_pk_add_f32 v[106:107], v[106:107], v[230:231]
	v_pk_add_f32 v[104:105], v[104:105], v[228:229]
	v_mov_b32_e32 v132, v131
	v_mov_b32_e32 v212, v131
	s_nop 1
	v_permlane32_swap_b32_e32 v132, v212
	s_waitcnt vmcnt(0)
	v_pk_mul_f32 v[126:127], v[246:247], v[126:127]
	v_pk_mul_f32 v[124:125], v[244:245], v[124:125]
	v_pk_mul_f32 v[122:123], v[246:247], v[122:123]
	v_pk_mul_f32 v[120:121], v[244:245], v[120:121]
	v_pk_mul_f32 v[114:115], v[246:247], v[114:115]
	v_pk_mul_f32 v[112:113], v[244:245], v[112:113]
	v_pk_mul_f32 v[106:107], v[246:247], v[106:107]
	v_pk_mul_f32 v[104:105], v[244:245], v[104:105]
	v_pk_fma_f32 v[126:127], v[166:167], s[34:35], v[126:127] op_sel_hi:[1,0,1]
	v_pk_fma_f32 v[124:125], v[164:165], s[34:35], v[124:125] op_sel_hi:[1,0,1]
	v_pk_fma_f32 v[122:123], v[186:187], s[34:35], v[122:123] op_sel_hi:[1,0,1]
	v_pk_fma_f32 v[120:121], v[184:185], s[34:35], v[120:121] op_sel_hi:[1,0,1]
	v_pk_fma_f32 v[114:115], v[162:163], s[34:35], v[114:115] op_sel_hi:[1,0,1]
	v_pk_fma_f32 v[112:113], v[160:161], s[34:35], v[112:113] op_sel_hi:[1,0,1]
	v_pk_fma_f32 v[106:107], v[190:191], s[34:35], v[106:107] op_sel_hi:[1,0,1]
	v_pk_fma_f32 v[104:105], v[188:189], s[34:35], v[104:105] op_sel_hi:[1,0,1]
	s_nop 0
	s_and_saveexec_b64 s[0:1], vcc
	s_cbranch_execz .LBB0_498
	s_lshl_b32 s39, s59, 11
	s_add_i32 s39, s7, s39
	v_mul_f32_e32 v134, 0x3c800000, v129
	v_lshl_add_u32 v129, v175, 5, s39
	s_waitcnt lgkmcnt(0)
	v_add_f32_e32 v135, v132, v212
	ds_write_b64 v129, v[134:135]
